# attention epilogue stores staged through LDS: 8 dwordx4 stores of full 256-byte rows instead of 16 scattered dwordx2
# speedup vs baseline: 1.0017x; 1.0017x over previous
.LBB0_582:
	s_or_b64 exec, exec, s[6:7]
	s_waitcnt lgkmcnt(0)
	s_barrier
	s_and_saveexec_b64 s[6:7], s[4:5]
	s_cbranch_execz .LBB0_556
	v_div_scale_f32 v5, s[10:11], v4, v4, 1.0
	v_rcp_f32_e32 v6, v5
	v_div_scale_f32 v7, vcc, 1.0, v4, 1.0
	v_readlane_b32 s12, v230, 34
	v_fma_f32 v8, -v5, v6, 1.0
	v_fmac_f32_e32 v6, v8, v6
	v_mul_f32_e32 v8, v7, v6
	v_fma_f32 v9, -v5, v8, v7
	v_fmac_f32_e32 v8, v9, v6
	v_fma_f32 v5, -v5, v8, v7
	v_div_fmas_f32 v5, v5, v6, v8
	v_div_fixup_f32 v80, v5, v4, 1.0
	ds_read2st64_b32 v[14:15], v3 offset1:1
	ds_read2st64_b32 v[88:89], v3 offset0:2 offset1:3
	ds_read2st64_b32 v[94:95], v3 offset0:4 offset1:5
	ds_read2st64_b32 v[92:93], v3 offset0:6 offset1:7
	ds_read2st64_b32 v[100:101], v3 offset0:8 offset1:9
	ds_read2st64_b32 v[102:103], v3 offset0:10 offset1:11
	ds_read2st64_b32 v[104:105], v3 offset0:12 offset1:13
	ds_read2st64_b32 v[106:107], v3 offset0:14 offset1:15
	ds_read2st64_b32 v[108:109], v3 offset0:16 offset1:17
	ds_read2st64_b32 v[110:111], v3 offset0:18 offset1:19
	ds_read2st64_b32 v[112:113], v3 offset0:20 offset1:21
	ds_read2st64_b32 v[114:115], v3 offset0:22 offset1:23
	ds_read2st64_b32 v[116:117], v3 offset0:24 offset1:25
	ds_read2st64_b32 v[118:119], v3 offset0:26 offset1:27
	ds_read2st64_b32 v[120:121], v3 offset0:28 offset1:29
	ds_read2st64_b32 v[122:123], v3 offset0:30 offset1:31
	ds_read2st64_b32 v[124:125], v3 offset0:32 offset1:33
	ds_read2st64_b32 v[126:127], v3 offset0:34 offset1:35
	ds_read2st64_b32 v[128:129], v3 offset0:36 offset1:37
	ds_read2st64_b32 v[130:131], v3 offset0:38 offset1:39
	ds_read2st64_b32 v[132:133], v3 offset0:40 offset1:41
	ds_read2st64_b32 v[134:135], v3 offset0:42 offset1:43
	ds_read2st64_b32 v[136:137], v3 offset0:44 offset1:45
	ds_read2st64_b32 v[138:139], v3 offset0:46 offset1:47
	ds_read2st64_b32 v[140:141], v3 offset0:56 offset1:57
	ds_read2st64_b32 v[142:143], v3 offset0:58 offset1:59
	ds_read2st64_b32 v[4:5], v3 offset0:60 offset1:61
	ds_read2st64_b32 v[8:9], v3 offset0:62 offset1:63
	ds_read2st64_b32 v[146:147], v3 offset0:48 offset1:49
	ds_read2st64_b32 v[174:175], v3 offset0:50 offset1:51
	ds_read2st64_b32 v[176:177], v3 offset0:52 offset1:53
	ds_read2st64_b32 v[178:179], v3 offset0:54 offset1:55
	s_add_i32 s79, s79, s60
	v_and_b32_e32 v3, 31, v2
	v_ashrrev_i32_e32 v2, 3, v2
	v_readlane_b32 s13, v230, 35
	s_waitcnt lgkmcnt(5)
	v_pk_fma_f32 v[6:7], v[28:29], v[80:81], v[4:5] op_sel_hi:[1,0,1] neg_lo:[0,0,1] neg_hi:[0,0,1]
	v_or3_b32 v86, v3, s79, v158
	v_and_b32_e32 v2, -4, v2
	v_mov_b64_e32 v[4:5], s[12:13]
	v_ashrrev_i32_e32 v3, 31, v2
	v_mad_u64_u32 v[4:5], s[10:11], v86, s33, v[4:5]
	v_lshl_add_u64 v[4:5], v[4:5], 0, s[22:23]
	v_lshlrev_b64 v[90:91], 1, v[2:3]
	v_lshl_add_u64 v[28:29], v[4:5], 0, v[90:91]
	s_mov_b64 s[10:11], 0x1800
	s_movk_i32 s8, 0x1000
	v_lshl_add_u64 v[12:13], v[28:29], 0, s[10:11]
	v_add_co_u32_e32 v28, vcc, s8, v28
	v_pk_fma_f32 v[182:183], v[64:65], v[80:81], v[14:15] op_sel_hi:[1,0,1] neg_lo:[0,0,1] neg_hi:[0,0,1]
	v_lshl_add_u64 v[10:11], v[2:3], 2, s[86:87]
	v_addc_co_u32_e32 v29, vcc, 0, v29, vcc
	v_pk_fma_f32 v[98:99], v[66:67], v[80:81], v[88:89] op_sel_hi:[1,0,1] neg_lo:[0,0,1] neg_hi:[0,0,1]
	v_pk_mul_f32 v[184:185], v[182:183], v[182:183]
	s_waitcnt lgkmcnt(4)
	v_pk_fma_f32 v[8:9], v[30:31], v[80:81], v[8:9] op_sel_hi:[1,0,1] neg_lo:[0,0,1] neg_hi:[0,0,1]
	global_load_dwordx4 v[2:5], v[10:11], off
	global_load_dwordx2 v[96:97], v[28:29], off offset:2048
	v_pk_mul_f32 v[180:181], v[98:99], v[98:99]
	v_pk_fma_f32 v[92:93], v[70:71], v[80:81], v[92:93] op_sel_hi:[1,0,1] neg_lo:[0,0,1] neg_hi:[0,0,1]
	v_pk_fma_f32 v[188:189], v[68:69], v[80:81], v[94:95] op_sel_hi:[1,0,1] neg_lo:[0,0,1] neg_hi:[0,0,1]
	v_pk_fma_f32 v[88:89], v[74:75], v[80:81], v[102:103] op_sel_hi:[1,0,1] neg_lo:[0,0,1] neg_hi:[0,0,1]
	v_pk_fma_f32 v[94:95], v[72:73], v[80:81], v[100:101] op_sel_hi:[1,0,1] neg_lo:[0,0,1] neg_hi:[0,0,1]
	v_pk_fma_f32 v[78:79], v[78:79], v[80:81], v[106:107] op_sel_hi:[1,0,1] neg_lo:[0,0,1] neg_hi:[0,0,1]
	v_pk_fma_f32 v[76:77], v[76:77], v[80:81], v[104:105] op_sel_hi:[1,0,1] neg_lo:[0,0,1] neg_hi:[0,0,1]
	v_pk_fma_f32 v[72:73], v[50:51], v[80:81], v[110:111] op_sel_hi:[1,0,1] neg_lo:[0,0,1] neg_hi:[0,0,1]
	v_pk_fma_f32 v[74:75], v[48:49], v[80:81], v[108:109] op_sel_hi:[1,0,1] neg_lo:[0,0,1] neg_hi:[0,0,1]
	v_pk_fma_f32 v[68:69], v[54:55], v[80:81], v[114:115] op_sel_hi:[1,0,1] neg_lo:[0,0,1] neg_hi:[0,0,1]
	v_pk_fma_f32 v[70:71], v[52:53], v[80:81], v[112:113] op_sel_hi:[1,0,1] neg_lo:[0,0,1] neg_hi:[0,0,1]
	v_pk_fma_f32 v[64:65], v[58:59], v[80:81], v[118:119] op_sel_hi:[1,0,1] neg_lo:[0,0,1] neg_hi:[0,0,1]
	v_pk_fma_f32 v[66:67], v[56:57], v[80:81], v[116:117] op_sel_hi:[1,0,1] neg_lo:[0,0,1] neg_hi:[0,0,1]
	v_pk_fma_f32 v[56:57], v[62:63], v[80:81], v[122:123] op_sel_hi:[1,0,1] neg_lo:[0,0,1] neg_hi:[0,0,1]
	v_pk_fma_f32 v[58:59], v[60:61], v[80:81], v[120:121] op_sel_hi:[1,0,1] neg_lo:[0,0,1] neg_hi:[0,0,1]
	v_pk_fma_f32 v[52:53], v[34:35], v[80:81], v[126:127] op_sel_hi:[1,0,1] neg_lo:[0,0,1] neg_hi:[0,0,1]
	v_pk_fma_f32 v[54:55], v[32:33], v[80:81], v[124:125] op_sel_hi:[1,0,1] neg_lo:[0,0,1] neg_hi:[0,0,1]
	v_pk_fma_f32 v[48:49], v[38:39], v[80:81], v[130:131] op_sel_hi:[1,0,1] neg_lo:[0,0,1] neg_hi:[0,0,1]
	v_pk_fma_f32 v[50:51], v[36:37], v[80:81], v[128:129] op_sel_hi:[1,0,1] neg_lo:[0,0,1] neg_hi:[0,0,1]
	v_pk_fma_f32 v[36:37], v[42:43], v[80:81], v[134:135] op_sel_hi:[1,0,1] neg_lo:[0,0,1] neg_hi:[0,0,1]
	v_pk_fma_f32 v[38:39], v[40:41], v[80:81], v[132:133] op_sel_hi:[1,0,1] neg_lo:[0,0,1] neg_hi:[0,0,1]
	v_pk_fma_f32 v[32:33], v[46:47], v[80:81], v[138:139] op_sel_hi:[1,0,1] neg_lo:[0,0,1] neg_hi:[0,0,1]
	v_pk_fma_f32 v[34:35], v[44:45], v[80:81], v[136:137] op_sel_hi:[1,0,1] neg_lo:[0,0,1] neg_hi:[0,0,1]
	s_waitcnt lgkmcnt(2)
	v_pk_fma_f32 v[28:29], v[18:19], v[80:81], v[174:175] op_sel_hi:[1,0,1] neg_lo:[0,0,1] neg_hi:[0,0,1]
	v_pk_fma_f32 v[30:31], v[16:17], v[80:81], v[146:147] op_sel_hi:[1,0,1] neg_lo:[0,0,1] neg_hi:[0,0,1]
	s_waitcnt lgkmcnt(0)
	v_pk_fma_f32 v[18:19], v[22:23], v[80:81], v[178:179] op_sel_hi:[1,0,1] neg_lo:[0,0,1] neg_hi:[0,0,1]
	v_pk_fma_f32 v[22:23], v[20:21], v[80:81], v[176:177] op_sel_hi:[1,0,1] neg_lo:[0,0,1] neg_hi:[0,0,1]
	v_pk_fma_f32 v[14:15], v[26:27], v[80:81], v[142:143] op_sel_hi:[1,0,1] neg_lo:[0,0,1] neg_hi:[0,0,1]
	v_pk_fma_f32 v[16:17], v[24:25], v[80:81], v[140:141] op_sel_hi:[1,0,1] neg_lo:[0,0,1] neg_hi:[0,0,1]
	v_add_f32_e32 v80, v184, v185
	v_add_f32_e32 v80, v80, v180
	v_pk_mul_f32 v[190:191], v[188:189], v[188:189]
	v_add_f32_e32 v80, v80, v181
	v_add_f32_e32 v80, v80, v190
	v_pk_mul_f32 v[186:187], v[92:93], v[92:93]
	v_add_f32_e32 v80, v80, v191
	v_add_f32_e32 v80, v80, v186
	v_pk_mul_f32 v[100:101], v[94:95], v[94:95]
	v_add_f32_e32 v80, v80, v187
	v_add_f32_e32 v80, v80, v100
	v_pk_mul_f32 v[102:103], v[88:89], v[88:89]
	v_add_f32_e32 v80, v80, v101
	v_add_f32_e32 v80, v80, v102
	v_pk_mul_f32 v[104:105], v[76:77], v[76:77]
	v_add_f32_e32 v80, v80, v103
	v_add_f32_e32 v80, v80, v104
	v_pk_mul_f32 v[106:107], v[78:79], v[78:79]
	v_add_f32_e32 v80, v80, v105
	v_add_f32_e32 v80, v80, v106
	v_pk_mul_f32 v[108:109], v[74:75], v[74:75]
	v_add_f32_e32 v80, v80, v107
	v_add_f32_e32 v80, v80, v108
	v_pk_mul_f32 v[110:111], v[72:73], v[72:73]
	v_add_f32_e32 v80, v80, v109
	v_add_f32_e32 v80, v80, v110
	v_pk_mul_f32 v[112:113], v[70:71], v[70:71]
	v_add_f32_e32 v80, v80, v111
	v_add_f32_e32 v80, v80, v112
	v_pk_mul_f32 v[114:115], v[68:69], v[68:69]
	v_add_f32_e32 v80, v80, v113
	v_add_f32_e32 v80, v80, v114
	v_pk_mul_f32 v[116:117], v[66:67], v[66:67]
	v_add_f32_e32 v80, v80, v115
	v_add_f32_e32 v80, v80, v116
	v_pk_mul_f32 v[118:119], v[64:65], v[64:65]
	v_add_f32_e32 v80, v80, v117
	v_add_f32_e32 v80, v80, v118
	v_pk_mul_f32 v[60:61], v[58:59], v[58:59]
	v_add_f32_e32 v80, v80, v119
	v_add_f32_e32 v60, v80, v60
	v_pk_mul_f32 v[62:63], v[56:57], v[56:57]
	v_add_f32_e32 v60, v60, v61
	v_add_f32_e32 v60, v60, v62
	v_pk_mul_f32 v[122:123], v[54:55], v[54:55]
	v_add_f32_e32 v60, v60, v63
	v_add_f32_e32 v60, v60, v122
	v_pk_mul_f32 v[120:121], v[52:53], v[52:53]
	v_add_f32_e32 v60, v60, v123
	v_add_f32_e32 v60, v60, v120
	v_pk_mul_f32 v[126:127], v[50:51], v[50:51]
	v_add_f32_e32 v60, v60, v121
	v_add_f32_e32 v60, v60, v126
	v_pk_mul_f32 v[124:125], v[48:49], v[48:49]
	v_add_f32_e32 v60, v60, v127
	v_add_f32_e32 v60, v60, v124
	v_pk_mul_f32 v[40:41], v[38:39], v[38:39]
	v_add_f32_e32 v60, v60, v125
	v_add_f32_e32 v40, v60, v40
	v_pk_mul_f32 v[42:43], v[36:37], v[36:37]
	v_add_f32_e32 v40, v40, v41
	v_add_f32_e32 v40, v40, v42
	v_pk_mul_f32 v[44:45], v[34:35], v[34:35]
	v_add_f32_e32 v40, v40, v43
	v_add_f32_e32 v40, v40, v44
	v_pk_mul_f32 v[46:47], v[32:33], v[32:33]
	v_add_f32_e32 v40, v40, v45
	v_add_f32_e32 v40, v40, v46
	v_pk_mul_f32 v[130:131], v[30:31], v[30:31]
	v_add_f32_e32 v40, v40, v47
	v_add_f32_e32 v40, v40, v130
	v_pk_mul_f32 v[128:129], v[28:29], v[28:29]
	v_add_f32_e32 v40, v40, v131
	v_add_f32_e32 v40, v40, v128
	v_pk_mul_f32 v[20:21], v[22:23], v[22:23]
	v_add_f32_e32 v40, v40, v129
	v_add_f32_e32 v20, v40, v20
	v_pk_mul_f32 v[132:133], v[18:19], v[18:19]
	v_add_f32_e32 v20, v20, v21
	v_add_f32_e32 v20, v20, v132
	v_pk_mul_f32 v[24:25], v[16:17], v[16:17]
	v_add_f32_e32 v20, v20, v133
	v_add_f32_e32 v20, v20, v24
	v_pk_mul_f32 v[26:27], v[14:15], v[14:15]
	v_add_f32_e32 v20, v20, v25
	v_add_f32_e32 v20, v20, v26
	v_pk_mul_f32 v[82:83], v[6:7], v[6:7]
	v_add_f32_e32 v20, v20, v27
	v_add_f32_e32 v20, v20, v82
	v_pk_mul_f32 v[84:85], v[8:9], v[8:9]
	v_add_f32_e32 v20, v20, v83
	v_add_f32_e32 v20, v20, v84
	v_add_f32_e32 v24, v20, v85
	ds_bpermute_b32 v1, v1, v24
	s_waitcnt vmcnt(0)
	v_and_b32_e32 v204, 31, v203
	v_lshrrev_b32_e32 v205, 5, v203
	v_mul_u32_u24_e32 v210, 0x110, v204
	v_lshl_add_u32 v210, v205, 3, v210
	v_add_u32_e32 v210, v172, v210
	v_lshrrev_b32_e32 v206, 4, v203
	v_and_b32_e32 v207, 15, v203
	v_mul_u32_u24_e32 v211, 0x110, v206
	v_lshl_add_u32 v211, v207, 4, v211
	v_add_u32_e32 v211, v172, v211
	v_sub_u32_e32 v206, v206, v204
	v_lshlrev_b32_e32 v206, 12, v206
	v_lshl_add_u32 v206, v207, 4, v206
	v_lshlrev_b32_e32 v205, 3, v205
	v_sub_u32_e32 v206, v206, v205
	v_ashrrev_i32_e32 v207, 31, v206
	v_lshlrev_b32_e32 v26, 16, v96
	v_and_b32_e32 v27, 0xffff0000, v96
	v_mov_b32_e32 v87, v0
	v_lshlrev_b64 v[20:21], 12, v[86:87]
	s_waitcnt lgkmcnt(0)
	v_add_f32_e32 v1, v24, v1
	v_fmamk_f32 v1, v1, 0x3c000000, v199
	v_mul_f32_e32 v24, 0x4b800000, v1
	v_cmp_gt_f32_e32 vcc, s3, v1
	v_lshlrev_b32_e32 v40, 16, v97
	v_and_b32_e32 v41, 0xffff0000, v97
	v_cndmask_b32_e32 v1, v1, v24, vcc
	v_rsq_f32_e32 v1, v1
	v_lshl_add_u64 v[20:21], s[94:95], 0, v[20:21]
	v_lshl_add_u64 v[20:21], v[20:21], 0, v[90:91]
	v_readlane_b32 s14, v230, 36
	v_mul_f32_e32 v24, 0x45800000, v1
	v_cndmask_b32_e32 v1, v1, v24, vcc
	v_mul_f32_e32 v24, v148, v1
	v_pk_mul_f32 v[42:43], v[182:183], v[24:25] op_sel_hi:[1,0]
	v_pk_mul_f32 v[38:39], v[38:39], v[24:25] op_sel_hi:[1,0]
	v_pk_mul_f32 v[2:3], v[2:3], v[42:43]
	v_pk_mul_f32 v[42:43], v[188:189], v[24:25] op_sel_hi:[1,0]
	v_pk_mul_f32 v[2:3], v[2:3], v[26:27]
	v_pk_mul_f32 v[26:27], v[98:99], v[24:25] op_sel_hi:[1,0]
	v_cvt_pk_bf16_f32 v2, v2, v3
	v_pk_mul_f32 v[4:5], v[4:5], v[26:27]
	v_pk_mul_f32 v[36:37], v[36:37], v[24:25] op_sel_hi:[1,0]
	v_pk_mul_f32 v[4:5], v[4:5], v[40:41]
	v_pk_mul_f32 v[34:35], v[34:35], v[24:25] op_sel_hi:[1,0]
	v_cvt_pk_bf16_f32 v3, v4, v5
	ds_write_b64 v210, v[2:3]
	global_load_dwordx2 v[26:27], v[12:13], off offset:16
	s_nop 0
	global_load_dwordx4 v[2:5], v[10:11], off offset:32
	v_pk_mul_f32 v[32:33], v[32:33], v[24:25] op_sel_hi:[1,0]
	v_pk_mul_f32 v[30:31], v[30:31], v[24:25] op_sel_hi:[1,0]
	v_pk_mul_f32 v[28:29], v[28:29], v[24:25] op_sel_hi:[1,0]
	v_pk_mul_f32 v[22:23], v[22:23], v[24:25] op_sel_hi:[1,0]
	v_pk_mul_f32 v[18:19], v[18:19], v[24:25] op_sel_hi:[1,0]
	v_pk_mul_f32 v[16:17], v[16:17], v[24:25] op_sel_hi:[1,0]
	v_pk_mul_f32 v[14:15], v[14:15], v[24:25] op_sel_hi:[1,0]
	v_pk_mul_f32 v[6:7], v[6:7], v[24:25] op_sel_hi:[1,0]
	v_pk_mul_f32 v[8:9], v[8:9], v[24:25] op_sel_hi:[1,0]
	v_readlane_b32 s15, v230, 37
	v_readlane_b32 s16, v230, 38
	v_readlane_b32 s17, v230, 39
	v_readlane_b32 s18, v230, 40
	v_readlane_b32 s19, v230, 41
	s_waitcnt vmcnt(1)
	v_lshlrev_b32_e32 v40, 16, v26
	s_waitcnt vmcnt(0)
	v_pk_mul_f32 v[2:3], v[2:3], v[42:43]
	v_and_b32_e32 v41, 0xffff0000, v26
	v_pk_mul_f32 v[2:3], v[2:3], v[40:41]
	v_pk_mul_f32 v[40:41], v[92:93], v[24:25] op_sel_hi:[1,0]
	v_lshlrev_b32_e32 v26, 16, v27
	v_pk_mul_f32 v[4:5], v[4:5], v[40:41]
	v_and_b32_e32 v27, 0xffff0000, v27
	v_pk_mul_f32 v[4:5], v[4:5], v[26:27]
	v_cvt_pk_bf16_f32 v2, v2, v3
	v_cvt_pk_bf16_f32 v3, v4, v5
	ds_write_b64 v210, v[2:3] offset:16
	global_load_dwordx2 v[26:27], v[12:13], off offset:32
	s_nop 0
	global_load_dwordx4 v[2:5], v[10:11], off offset:64
	v_pk_mul_f32 v[40:41], v[94:95], v[24:25] op_sel_hi:[1,0]
	v_pk_mul_f32 v[42:43], v[88:89], v[24:25] op_sel_hi:[1,0]
	s_waitcnt vmcnt(1)
	v_lshlrev_b32_e32 v44, 16, v26
	s_waitcnt vmcnt(0)
	v_pk_mul_f32 v[2:3], v[2:3], v[40:41]
	v_and_b32_e32 v45, 0xffff0000, v26
	v_lshlrev_b32_e32 v26, 16, v27
	v_pk_mul_f32 v[4:5], v[4:5], v[42:43]
	v_and_b32_e32 v27, 0xffff0000, v27
	v_pk_mul_f32 v[2:3], v[2:3], v[44:45]
	v_pk_mul_f32 v[4:5], v[4:5], v[26:27]
	v_cvt_pk_bf16_f32 v2, v2, v3
	v_cvt_pk_bf16_f32 v3, v4, v5
	ds_write_b64 v210, v[2:3] offset:32
	global_load_dwordx2 v[26:27], v[12:13], off offset:48
	s_nop 0
	global_load_dwordx4 v[2:5], v[10:11], off offset:96
	v_pk_mul_f32 v[40:41], v[76:77], v[24:25] op_sel_hi:[1,0]
	v_pk_mul_f32 v[42:43], v[78:79], v[24:25] op_sel_hi:[1,0]
	s_waitcnt vmcnt(1)
	v_lshlrev_b32_e32 v44, 16, v26
	s_waitcnt vmcnt(0)
	v_pk_mul_f32 v[2:3], v[40:41], v[2:3]
	v_and_b32_e32 v45, 0xffff0000, v26
	v_lshlrev_b32_e32 v26, 16, v27
	v_pk_mul_f32 v[4:5], v[42:43], v[4:5]
	v_and_b32_e32 v27, 0xffff0000, v27
	v_pk_mul_f32 v[2:3], v[2:3], v[44:45]
	v_pk_mul_f32 v[4:5], v[4:5], v[26:27]
	v_cvt_pk_bf16_f32 v2, v2, v3
	v_cvt_pk_bf16_f32 v3, v4, v5
	ds_write_b64 v210, v[2:3] offset:48
	global_load_dwordx2 v[26:27], v[12:13], off offset:64
	s_nop 0
	global_load_dwordx4 v[2:5], v[10:11], off offset:128
	v_pk_mul_f32 v[40:41], v[74:75], v[24:25] op_sel_hi:[1,0]
	v_pk_mul_f32 v[42:43], v[72:73], v[24:25] op_sel_hi:[1,0]
	s_waitcnt vmcnt(1)
	v_lshlrev_b32_e32 v44, 16, v26
	s_waitcnt vmcnt(0)
	v_pk_mul_f32 v[2:3], v[40:41], v[2:3]
	v_and_b32_e32 v45, 0xffff0000, v26
	v_lshlrev_b32_e32 v26, 16, v27
	v_pk_mul_f32 v[4:5], v[42:43], v[4:5]
	v_and_b32_e32 v27, 0xffff0000, v27
	v_pk_mul_f32 v[2:3], v[2:3], v[44:45]
	v_pk_mul_f32 v[4:5], v[4:5], v[26:27]
	v_cvt_pk_bf16_f32 v2, v2, v3
	v_cvt_pk_bf16_f32 v3, v4, v5
	ds_write_b64 v210, v[2:3] offset:64
	global_load_dwordx2 v[26:27], v[12:13], off offset:80
	s_nop 0
	global_load_dwordx4 v[2:5], v[10:11], off offset:160
	v_pk_mul_f32 v[40:41], v[70:71], v[24:25] op_sel_hi:[1,0]
	v_pk_mul_f32 v[42:43], v[68:69], v[24:25] op_sel_hi:[1,0]
	s_waitcnt vmcnt(1)
	v_lshlrev_b32_e32 v44, 16, v26
	s_waitcnt vmcnt(0)
	v_pk_mul_f32 v[2:3], v[40:41], v[2:3]
	v_and_b32_e32 v45, 0xffff0000, v26
	v_lshlrev_b32_e32 v26, 16, v27
	v_pk_mul_f32 v[4:5], v[42:43], v[4:5]
	v_and_b32_e32 v27, 0xffff0000, v27
	v_pk_mul_f32 v[2:3], v[2:3], v[44:45]
	v_pk_mul_f32 v[4:5], v[4:5], v[26:27]
	v_cvt_pk_bf16_f32 v2, v2, v3
	v_cvt_pk_bf16_f32 v3, v4, v5
	ds_write_b64 v210, v[2:3] offset:80
	global_load_dwordx2 v[26:27], v[12:13], off offset:96
	s_nop 0
	global_load_dwordx4 v[2:5], v[10:11], off offset:192
	v_pk_mul_f32 v[40:41], v[66:67], v[24:25] op_sel_hi:[1,0]
	v_pk_mul_f32 v[42:43], v[64:65], v[24:25] op_sel_hi:[1,0]
	s_waitcnt vmcnt(1)
	v_lshlrev_b32_e32 v44, 16, v26
	s_waitcnt vmcnt(0)
	v_pk_mul_f32 v[2:3], v[40:41], v[2:3]
	v_and_b32_e32 v45, 0xffff0000, v26
	v_lshlrev_b32_e32 v26, 16, v27
	v_pk_mul_f32 v[4:5], v[42:43], v[4:5]
	v_and_b32_e32 v27, 0xffff0000, v27
	v_pk_mul_f32 v[2:3], v[2:3], v[44:45]
	v_pk_mul_f32 v[4:5], v[4:5], v[26:27]
	v_cvt_pk_bf16_f32 v2, v2, v3
	v_cvt_pk_bf16_f32 v3, v4, v5
	ds_write_b64 v210, v[2:3] offset:96
	global_load_dwordx2 v[26:27], v[12:13], off offset:112
	s_nop 0
	global_load_dwordx4 v[2:5], v[10:11], off offset:224
	v_pk_mul_f32 v[40:41], v[58:59], v[24:25] op_sel_hi:[1,0]
	v_pk_mul_f32 v[42:43], v[56:57], v[24:25] op_sel_hi:[1,0]
	s_waitcnt vmcnt(1)
	v_lshlrev_b32_e32 v44, 16, v26
	s_waitcnt vmcnt(0)
	v_pk_mul_f32 v[2:3], v[40:41], v[2:3]
	v_and_b32_e32 v45, 0xffff0000, v26
	v_lshlrev_b32_e32 v26, 16, v27
	v_pk_mul_f32 v[4:5], v[42:43], v[4:5]
	v_and_b32_e32 v27, 0xffff0000, v27
	v_pk_mul_f32 v[2:3], v[2:3], v[44:45]
	v_pk_mul_f32 v[4:5], v[4:5], v[26:27]
	v_cvt_pk_bf16_f32 v2, v2, v3
	v_cvt_pk_bf16_f32 v3, v4, v5
	ds_write_b64 v210, v[2:3] offset:112
	global_load_dwordx2 v[26:27], v[12:13], off offset:128
	s_nop 0
	global_load_dwordx4 v[2:5], v[10:11], off offset:256
	v_pk_mul_f32 v[40:41], v[54:55], v[24:25] op_sel_hi:[1,0]
	v_pk_mul_f32 v[42:43], v[52:53], v[24:25] op_sel_hi:[1,0]
	s_waitcnt vmcnt(1)
	v_lshlrev_b32_e32 v44, 16, v26
	s_waitcnt vmcnt(0)
	v_pk_mul_f32 v[2:3], v[40:41], v[2:3]
	v_and_b32_e32 v45, 0xffff0000, v26
	v_lshlrev_b32_e32 v26, 16, v27
	v_pk_mul_f32 v[4:5], v[42:43], v[4:5]
	v_and_b32_e32 v27, 0xffff0000, v27
	v_pk_mul_f32 v[2:3], v[2:3], v[44:45]
	v_pk_mul_f32 v[4:5], v[4:5], v[26:27]
	v_cvt_pk_bf16_f32 v2, v2, v3
	v_cvt_pk_bf16_f32 v3, v4, v5
	ds_write_b64 v210, v[2:3] offset:128
	global_load_dwordx2 v[26:27], v[12:13], off offset:144
	s_nop 0
	global_load_dwordx4 v[2:5], v[10:11], off offset:288
	v_pk_mul_f32 v[40:41], v[50:51], v[24:25] op_sel_hi:[1,0]
	v_pk_mul_f32 v[42:43], v[48:49], v[24:25] op_sel_hi:[1,0]
	s_waitcnt vmcnt(1)
	v_lshlrev_b32_e32 v44, 16, v26
	s_waitcnt vmcnt(0)
	v_pk_mul_f32 v[2:3], v[40:41], v[2:3]
	v_and_b32_e32 v45, 0xffff0000, v26
	v_lshlrev_b32_e32 v26, 16, v27
	v_pk_mul_f32 v[4:5], v[42:43], v[4:5]
	v_and_b32_e32 v27, 0xffff0000, v27
	v_pk_mul_f32 v[2:3], v[2:3], v[44:45]
	v_pk_mul_f32 v[4:5], v[4:5], v[26:27]
	v_cvt_pk_bf16_f32 v2, v2, v3
	v_cvt_pk_bf16_f32 v3, v4, v5
	ds_write_b64 v210, v[2:3] offset:144
	global_load_dwordx2 v[26:27], v[12:13], off offset:160
	s_nop 0
	global_load_dwordx4 v[2:5], v[10:11], off offset:320
	s_waitcnt vmcnt(1)
	v_lshlrev_b32_e32 v40, 16, v26
	s_waitcnt vmcnt(0)
	v_pk_mul_f32 v[2:3], v[38:39], v[2:3]
	v_and_b32_e32 v41, 0xffff0000, v26
	v_lshlrev_b32_e32 v26, 16, v27
	v_pk_mul_f32 v[4:5], v[36:37], v[4:5]
	v_and_b32_e32 v27, 0xffff0000, v27
	v_pk_mul_f32 v[2:3], v[2:3], v[40:41]
	v_pk_mul_f32 v[4:5], v[4:5], v[26:27]
	v_cvt_pk_bf16_f32 v2, v2, v3
	v_cvt_pk_bf16_f32 v3, v4, v5
	ds_write_b64 v210, v[2:3] offset:160
	global_load_dwordx2 v[26:27], v[12:13], off offset:176
	s_nop 0
	global_load_dwordx4 v[2:5], v[10:11], off offset:352
	s_waitcnt vmcnt(1)
	v_lshlrev_b32_e32 v36, 16, v26
	s_waitcnt vmcnt(0)
	v_pk_mul_f32 v[2:3], v[34:35], v[2:3]
	v_and_b32_e32 v37, 0xffff0000, v26
	v_lshlrev_b32_e32 v26, 16, v27
	v_pk_mul_f32 v[4:5], v[32:33], v[4:5]
	v_and_b32_e32 v27, 0xffff0000, v27
	v_pk_mul_f32 v[2:3], v[2:3], v[36:37]
	v_pk_mul_f32 v[4:5], v[4:5], v[26:27]
	v_cvt_pk_bf16_f32 v2, v2, v3
	v_cvt_pk_bf16_f32 v3, v4, v5
	ds_write_b64 v210, v[2:3] offset:176
	global_load_dwordx2 v[26:27], v[12:13], off offset:192
	s_nop 0
	global_load_dwordx4 v[2:5], v[10:11], off offset:384
	s_waitcnt vmcnt(1)
	v_lshlrev_b32_e32 v32, 16, v26
	s_waitcnt vmcnt(0)
	v_pk_mul_f32 v[2:3], v[30:31], v[2:3]
	v_and_b32_e32 v33, 0xffff0000, v26
	v_lshlrev_b32_e32 v26, 16, v27
	v_pk_mul_f32 v[4:5], v[28:29], v[4:5]
	v_and_b32_e32 v27, 0xffff0000, v27
	v_pk_mul_f32 v[2:3], v[2:3], v[32:33]
	v_pk_mul_f32 v[4:5], v[4:5], v[26:27]
	v_cvt_pk_bf16_f32 v2, v2, v3
	v_cvt_pk_bf16_f32 v3, v4, v5
	ds_write_b64 v210, v[2:3] offset:192
	global_load_dwordx2 v[26:27], v[12:13], off offset:208
	s_nop 0
	global_load_dwordx4 v[2:5], v[10:11], off offset:416
	s_waitcnt vmcnt(1)
	v_lshlrev_b32_e32 v28, 16, v26
	s_waitcnt vmcnt(0)
	v_pk_mul_f32 v[2:3], v[22:23], v[2:3]
	v_and_b32_e32 v29, 0xffff0000, v26
	v_lshlrev_b32_e32 v22, 16, v27
	v_pk_mul_f32 v[4:5], v[18:19], v[4:5]
	v_and_b32_e32 v23, 0xffff0000, v27
	v_pk_mul_f32 v[2:3], v[2:3], v[28:29]
	v_pk_mul_f32 v[4:5], v[4:5], v[22:23]
	v_cvt_pk_bf16_f32 v2, v2, v3
	v_cvt_pk_bf16_f32 v3, v4, v5
	ds_write_b64 v210, v[2:3] offset:208
	global_load_dwordx2 v[18:19], v[12:13], off offset:224
	s_nop 0
	global_load_dwordx4 v[2:5], v[10:11], off offset:448
	s_waitcnt vmcnt(1)
	v_lshlrev_b32_e32 v22, 16, v18
	s_waitcnt vmcnt(0)
	v_pk_mul_f32 v[2:3], v[16:17], v[2:3]
	v_and_b32_e32 v23, 0xffff0000, v18
	v_lshlrev_b32_e32 v16, 16, v19
	v_pk_mul_f32 v[4:5], v[14:15], v[4:5]
	v_and_b32_e32 v17, 0xffff0000, v19
	v_pk_mul_f32 v[2:3], v[2:3], v[22:23]
	v_pk_mul_f32 v[4:5], v[4:5], v[16:17]
	v_cvt_pk_bf16_f32 v2, v2, v3
	v_cvt_pk_bf16_f32 v3, v4, v5
	ds_write_b64 v210, v[2:3] offset:224
	global_load_dwordx2 v[12:13], v[12:13], off offset:240
	s_nop 0
	global_load_dwordx4 v[2:5], v[10:11], off offset:480
	s_waitcnt vmcnt(1)
	v_lshlrev_b32_e32 v10, 16, v12
	v_and_b32_e32 v11, 0xffff0000, v12
	s_waitcnt vmcnt(0)
	v_pk_mul_f32 v[2:3], v[6:7], v[2:3]
	v_lshlrev_b32_e32 v6, 16, v13
	v_and_b32_e32 v7, 0xffff0000, v13
	v_pk_mul_f32 v[4:5], v[8:9], v[4:5]
	v_pk_mul_f32 v[2:3], v[2:3], v[10:11]
	v_pk_mul_f32 v[4:5], v[4:5], v[6:7]
	v_cvt_pk_bf16_f32 v2, v2, v3
	v_cvt_pk_bf16_f32 v3, v4, v5
	ds_write_b64 v210, v[2:3] offset:240
	v_lshl_add_u64 v[208:209], v[20:21], 0, v[206:207]
	s_waitcnt lgkmcnt(0)
	ds_read_b128 v[100:103], v211
	ds_read_b128 v[104:107], v211 offset:1088
	ds_read_b128 v[108:111], v211 offset:2176
	ds_read_b128 v[112:115], v211 offset:3264
	ds_read_b128 v[116:119], v211 offset:4352
	ds_read_b128 v[120:123], v211 offset:5440
	ds_read_b128 v[124:127], v211 offset:6528
	ds_read_b128 v[128:131], v211 offset:7616
	s_waitcnt lgkmcnt(7)
	global_store_dwordx4 v[208:209], v[100:103], off
	v_add_co_u32_e32 v208, vcc, 0x4000, v208
	s_nop 1
	v_addc_co_u32_e32 v209, vcc, 0, v209, vcc
	s_waitcnt lgkmcnt(6)
	global_store_dwordx4 v[208:209], v[104:107], off
	v_add_co_u32_e32 v208, vcc, 0x4000, v208
	s_nop 1
	v_addc_co_u32_e32 v209, vcc, 0, v209, vcc
	s_waitcnt lgkmcnt(5)
	global_store_dwordx4 v[208:209], v[108:111], off
	v_add_co_u32_e32 v208, vcc, 0x4000, v208
	s_nop 1
	v_addc_co_u32_e32 v209, vcc, 0, v209, vcc
	s_waitcnt lgkmcnt(4)
	global_store_dwordx4 v[208:209], v[112:115], off
	v_add_co_u32_e32 v208, vcc, 0x4000, v208
	s_nop 1
	v_addc_co_u32_e32 v209, vcc, 0, v209, vcc
	s_waitcnt lgkmcnt(3)
	global_store_dwordx4 v[208:209], v[116:119], off
	v_add_co_u32_e32 v208, vcc, 0x4000, v208
	s_nop 1
	v_addc_co_u32_e32 v209, vcc, 0, v209, vcc
	s_waitcnt lgkmcnt(2)
	global_store_dwordx4 v[208:209], v[120:123], off
	v_add_co_u32_e32 v208, vcc, 0x4000, v208
	s_nop 1
	v_addc_co_u32_e32 v209, vcc, 0, v209, vcc
	s_waitcnt lgkmcnt(1)
	global_store_dwordx4 v[208:209], v[124:127], off
	v_add_co_u32_e32 v208, vcc, 0x4000, v208
	s_nop 1
	v_addc_co_u32_e32 v209, vcc, 0, v209, vcc
	s_waitcnt lgkmcnt(0)
	global_store_dwordx4 v[208:209], v[128:131], off
	s_branch .LBB0_556
